# v6 stack plus LDS-DMA loads in the GEMM loops use the saddr form (per-load 64-bit VALU address add dropped)
# speedup vs baseline: 1.0109x; 1.0109x over previous
.LBB0_218:
	s_add_u32 s36, s18, s46
	s_addc_u32 s37, s19, s47
	s_add_u32 s36, s36, 0x100
	s_addc_u32 s37, s37, 0
	s_add_u32 s48, s24, s46
	s_addc_u32 s49, s25, s47
	s_add_i32 s50, 0, 0x10000
	v_add_u32_e32 v160, s50, v146
	ds_read_b128 v[148:151], v160
	ds_read_b128 v[152:155], v160 offset:1024
	ds_read_b128 v[156:159], v160 offset:2048
	ds_read_b128 v[160:163], v160 offset:3072
	s_cmpk_eq_i32 s46, 0x1f00
	s_cselect_b32 s87, s23, s37
	s_cselect_b32 s86, vcc_lo, s36
	s_cselect_b32 s49, s21, s49
	s_cselect_b32 s48, vcc_hi, s48
	v_lshl_add_u64 v[196:197], v[142:143], 0, s[46:47]
	s_add_i32 m0, s91, 0xc000
	ds_read_b128 v[164:167], v147
	ds_read_b128 v[168:171], v147 offset:1024
	ds_read_b128 v[172:175], v147 offset:2048
	ds_read_b128 v[176:179], v147 offset:3072
	ds_read_b128 v[180:183], v147 offset:4096
	ds_read_b128 v[184:187], v147 offset:5120
	ds_read_b128 v[188:191], v147 offset:6144
	ds_read_b128 v[192:195], v147 offset:7168
	global_load_lds_dwordx4 v[196:197], off
	v_lshl_add_u64 v[196:197], v[144:145], 0, s[46:47]
	s_add_i32 m0, s91, 0xe000
	s_nop 0
	global_load_lds_dwordx4 v[196:197], off
	s_waitcnt lgkmcnt(8)
	s_barrier
	s_waitcnt lgkmcnt(0)
	s_waitcnt lgkmcnt(0)
	v_mfma_f32_16x16x32_bf16 v[126:129], v[148:151], v[164:167], v[126:129]
	v_mfma_f32_16x16x32_bf16 v[122:125], v[156:159], v[164:167], v[122:125]
	v_mfma_f32_16x16x32_bf16 v[110:113], v[148:151], v[172:175], v[110:113]
	v_mfma_f32_16x16x32_bf16 v[106:109], v[156:159], v[172:175], v[106:109]
	v_mfma_f32_16x16x32_bf16 v[98:101], v[148:151], v[180:183], v[98:101]
	v_mfma_f32_16x16x32_bf16 v[90:93], v[156:159], v[180:183], v[90:93]
	v_mfma_f32_16x16x32_bf16 v[82:85], v[148:151], v[188:191], v[82:85]
	v_mfma_f32_16x16x32_bf16 v[74:77], v[156:159], v[188:191], v[74:77]
	v_mfma_f32_16x16x32_bf16 v[126:129], v[152:155], v[168:171], v[126:129]
	v_mfma_f32_16x16x32_bf16 v[122:125], v[160:163], v[168:171], v[122:125]
	v_mfma_f32_16x16x32_bf16 v[110:113], v[152:155], v[176:179], v[110:113]
	v_mfma_f32_16x16x32_bf16 v[106:109], v[160:163], v[176:179], v[106:109]
	v_mfma_f32_16x16x32_bf16 v[98:101], v[152:155], v[184:187], v[98:101]
	v_mfma_f32_16x16x32_bf16 v[90:93], v[160:163], v[184:187], v[90:93]
	v_mfma_f32_16x16x32_bf16 v[82:85], v[152:155], v[192:195], v[82:85]
	v_mfma_f32_16x16x32_bf16 v[74:77], v[160:163], v[192:195], v[74:77]
	s_barrier
	s_add_i32 s31, 0, 0x14000
	v_add_u32_e32 v200, s31, v146
	s_add_i32 s36, s50, s90
	ds_read_b128 v[196:199], v200
	ds_read_b128 v[216:219], v200 offset:1024
	ds_read_b128 v[232:235], v200 offset:2048
	ds_read_b128 v[236:239], v200 offset:3072
	v_lshl_add_u64 v[200:201], s[48:49], 0, v[134:135]
	s_mov_b32 m0, s36
	v_lshl_add_u64 v[204:205], s[48:49], 0, v[130:131]
	global_load_lds_dwordx4 v[200:201], off
	s_add_i32 m0, s36, 0x2000
	s_nop 0
	global_load_lds_dwordx4 v[204:205], off
	s_barrier
	s_waitcnt lgkmcnt(0)
	s_waitcnt lgkmcnt(0)
	v_mfma_f32_16x16x32_bf16 v[118:121], v[196:199], v[164:167], v[118:121]
	v_mfma_f32_16x16x32_bf16 v[114:117], v[232:235], v[164:167], v[114:117]
	v_mfma_f32_16x16x32_bf16 v[102:105], v[196:199], v[172:175], v[102:105]
	v_mfma_f32_16x16x32_bf16 v[94:97], v[232:235], v[172:175], v[94:97]
	v_mfma_f32_16x16x32_bf16 v[86:89], v[196:199], v[180:183], v[86:89]
	v_mfma_f32_16x16x32_bf16 v[78:81], v[232:235], v[180:183], v[78:81]
	v_mfma_f32_16x16x32_bf16 v[70:73], v[196:199], v[188:191], v[70:73]
	v_mfma_f32_16x16x32_bf16 v[66:69], v[232:235], v[188:191], v[66:69]
	v_mfma_f32_16x16x32_bf16 v[118:121], v[216:219], v[168:171], v[118:121]
	v_mfma_f32_16x16x32_bf16 v[114:117], v[236:239], v[168:171], v[114:117]
	v_mfma_f32_16x16x32_bf16 v[102:105], v[216:219], v[176:179], v[102:105]
	v_mfma_f32_16x16x32_bf16 v[94:97], v[236:239], v[176:179], v[94:97]
	v_mfma_f32_16x16x32_bf16 v[86:89], v[216:219], v[184:187], v[86:89]
	v_mfma_f32_16x16x32_bf16 v[78:81], v[236:239], v[184:187], v[78:81]
	v_mfma_f32_16x16x32_bf16 v[70:73], v[216:219], v[192:195], v[70:73]
	v_mfma_f32_16x16x32_bf16 v[66:69], v[236:239], v[192:195], v[66:69]
	s_mov_b32 m0, s91
	v_lshl_add_u64 v[240:241], s[86:87], 0, v[136:137]
	s_barrier
	ds_read_b128 v[164:167], v147 offset:16384
	ds_read_b128 v[168:171], v147 offset:17408
	ds_read_b128 v[172:175], v147 offset:18432
	ds_read_b128 v[176:179], v147 offset:19456
	ds_read_b128 v[180:183], v147 offset:20480
	ds_read_b128 v[184:187], v147 offset:21504
	ds_read_b128 v[188:191], v147 offset:22528
	ds_read_b128 v[192:195], v147 offset:23552
	global_load_lds_dwordx4 v[240:241], off
	v_lshl_add_u64 v[242:243], s[86:87], 0, v[132:133]
	s_mov_b32 m0, s97
	s_nop 0
	global_load_lds_dwordx4 v[242:243], off
	s_barrier
	s_waitcnt lgkmcnt(0)
	s_waitcnt lgkmcnt(0)
	v_mfma_f32_16x16x32_bf16 v[62:65], v[148:151], v[164:167], v[62:65]
	v_mfma_f32_16x16x32_bf16 v[58:61], v[156:159], v[164:167], v[58:61]
	v_mfma_f32_16x16x32_bf16 v[50:53], v[148:151], v[172:175], v[50:53]
	v_mfma_f32_16x16x32_bf16 v[42:45], v[156:159], v[172:175], v[42:45]
	v_mfma_f32_16x16x32_bf16 v[34:37], v[148:151], v[180:183], v[34:37]
	v_mfma_f32_16x16x32_bf16 v[26:29], v[156:159], v[180:183], v[26:29]
	v_mfma_f32_16x16x32_bf16 v[18:21], v[148:151], v[188:191], v[18:21]
	v_mfma_f32_16x16x32_bf16 v[10:13], v[156:159], v[188:191], v[10:13]
	v_mfma_f32_16x16x32_bf16 v[62:65], v[152:155], v[168:171], v[62:65]
	v_mfma_f32_16x16x32_bf16 v[58:61], v[160:163], v[168:171], v[58:61]
	v_mfma_f32_16x16x32_bf16 v[50:53], v[152:155], v[176:179], v[50:53]
	v_mfma_f32_16x16x32_bf16 v[42:45], v[160:163], v[176:179], v[42:45]
	v_mfma_f32_16x16x32_bf16 v[34:37], v[152:155], v[184:187], v[34:37]
	v_mfma_f32_16x16x32_bf16 v[26:29], v[160:163], v[184:187], v[26:29]
	v_mfma_f32_16x16x32_bf16 v[18:21], v[152:155], v[192:195], v[18:21]
	v_mfma_f32_16x16x32_bf16 v[10:13], v[160:163], v[192:195], v[10:13]
	s_barrier
	s_add_u32 s36, s48, 0x100000
	s_addc_u32 s37, s49, 0
	s_add_i32 s31, s31, s90
	s_mov_b32 m0, s31
	s_nop 0
	global_load_lds_dwordx4 v134, s[36:37]
	s_add_i32 m0, s31, 0x2000
	s_nop 0
	global_load_lds_dwordx4 v130, s[36:37]
	s_waitcnt vmcnt(6)
	s_barrier
	v_mfma_f32_16x16x32_bf16 v[54:57], v[196:199], v[164:167], v[54:57]
	v_mfma_f32_16x16x32_bf16 v[46:49], v[232:235], v[164:167], v[46:49]
	v_mfma_f32_16x16x32_bf16 v[38:41], v[196:199], v[172:175], v[38:41]
	v_mfma_f32_16x16x32_bf16 v[30:33], v[232:235], v[172:175], v[30:33]
	v_mfma_f32_16x16x32_bf16 v[22:25], v[196:199], v[180:183], v[22:25]
	v_mfma_f32_16x16x32_bf16 v[14:17], v[232:235], v[180:183], v[14:17]
	v_mfma_f32_16x16x32_bf16 v[6:9], v[196:199], v[188:191], v[6:9]
	v_mfma_f32_16x16x32_bf16 v[2:5], v[232:235], v[188:191], v[2:5]
	v_mfma_f32_16x16x32_bf16 v[54:57], v[216:219], v[168:171], v[54:57]
	v_mfma_f32_16x16x32_bf16 v[46:49], v[236:239], v[168:171], v[46:49]
	v_mfma_f32_16x16x32_bf16 v[38:41], v[216:219], v[176:179], v[38:41]
	v_mfma_f32_16x16x32_bf16 v[30:33], v[236:239], v[176:179], v[30:33]
	v_mfma_f32_16x16x32_bf16 v[22:25], v[216:219], v[184:187], v[22:25]
	v_mfma_f32_16x16x32_bf16 v[14:17], v[236:239], v[184:187], v[14:17]
	v_mfma_f32_16x16x32_bf16 v[6:9], v[216:219], v[192:195], v[6:9]
	v_mfma_f32_16x16x32_bf16 v[2:5], v[236:239], v[192:195], v[2:5]
	s_add_i32 s31, 0, 0x18000
	v_add_u32_e32 v160, s31, v146
	s_barrier
	ds_read_b128 v[148:151], v160
	ds_read_b128 v[152:155], v160 offset:1024
	ds_read_b128 v[156:159], v160 offset:2048
	ds_read_b128 v[160:163], v160 offset:3072
	s_add_u32 s36, s86, 0x100000
	s_addc_u32 s37, s87, 0
	s_mov_b32 m0, s96
	ds_read_b128 v[164:167], v147 offset:32768
	ds_read_b128 v[168:171], v147 offset:33792
	ds_read_b128 v[172:175], v147 offset:34816
	ds_read_b128 v[176:179], v147 offset:35840
	ds_read_b128 v[180:183], v147 offset:36864
	ds_read_b128 v[184:187], v147 offset:37888
	ds_read_b128 v[188:191], v147 offset:38912
	ds_read_b128 v[192:195], v147 offset:39936
	global_load_lds_dwordx4 v136, s[36:37]
	s_mov_b32 m0, s80
	s_nop 0
	global_load_lds_dwordx4 v132, s[36:37]
	s_waitcnt lgkmcnt(8)
	s_barrier
	s_waitcnt lgkmcnt(0)
	s_waitcnt lgkmcnt(0)
	v_mfma_f32_16x16x32_bf16 v[126:129], v[148:151], v[164:167], v[126:129]
	v_mfma_f32_16x16x32_bf16 v[122:125], v[156:159], v[164:167], v[122:125]
	v_mfma_f32_16x16x32_bf16 v[110:113], v[148:151], v[172:175], v[110:113]
	v_mfma_f32_16x16x32_bf16 v[106:109], v[156:159], v[172:175], v[106:109]
	v_mfma_f32_16x16x32_bf16 v[98:101], v[148:151], v[180:183], v[98:101]
	v_mfma_f32_16x16x32_bf16 v[90:93], v[156:159], v[180:183], v[90:93]
	v_mfma_f32_16x16x32_bf16 v[82:85], v[148:151], v[188:191], v[82:85]
	v_mfma_f32_16x16x32_bf16 v[74:77], v[156:159], v[188:191], v[74:77]
	v_mfma_f32_16x16x32_bf16 v[126:129], v[152:155], v[168:171], v[126:129]
	v_mfma_f32_16x16x32_bf16 v[122:125], v[160:163], v[168:171], v[122:125]
	v_mfma_f32_16x16x32_bf16 v[110:113], v[152:155], v[176:179], v[110:113]
	v_mfma_f32_16x16x32_bf16 v[106:109], v[160:163], v[176:179], v[106:109]
	v_mfma_f32_16x16x32_bf16 v[98:101], v[152:155], v[184:187], v[98:101]
	v_mfma_f32_16x16x32_bf16 v[90:93], v[160:163], v[184:187], v[90:93]
	v_mfma_f32_16x16x32_bf16 v[82:85], v[152:155], v[192:195], v[82:85]
	v_mfma_f32_16x16x32_bf16 v[74:77], v[160:163], v[192:195], v[74:77]
	s_barrier
	s_add_i32 s50, 0, 0x1c000
	s_add_i32 s31, s31, s90
	v_add_u32_e32 v203, s50, v146
	v_lshl_add_u64 v[200:201], v[200:201], 0, s[14:15]
	s_mov_b32 m0, s31
	ds_read_b128 v[196:199], v203
	ds_read_b128 v[216:219], v203 offset:1024
	ds_read_b128 v[232:235], v203 offset:2048
	ds_read_b128 v[236:239], v203 offset:3072
	global_load_lds_dwordx4 v[200:201], off
	v_lshl_add_u64 v[200:201], v[204:205], 0, s[14:15]
	s_add_i32 m0, s31, 0x2000
	s_nop 0
	global_load_lds_dwordx4 v[200:201], off
	s_barrier
	s_waitcnt lgkmcnt(0)
	s_waitcnt lgkmcnt(0)
	v_mfma_f32_16x16x32_bf16 v[118:121], v[196:199], v[164:167], v[118:121]
	v_mfma_f32_16x16x32_bf16 v[114:117], v[232:235], v[164:167], v[114:117]
	v_mfma_f32_16x16x32_bf16 v[102:105], v[196:199], v[172:175], v[102:105]
	v_mfma_f32_16x16x32_bf16 v[94:97], v[232:235], v[172:175], v[94:97]
	v_mfma_f32_16x16x32_bf16 v[86:89], v[196:199], v[180:183], v[86:89]
	v_mfma_f32_16x16x32_bf16 v[78:81], v[232:235], v[180:183], v[78:81]
	v_mfma_f32_16x16x32_bf16 v[70:73], v[196:199], v[188:191], v[70:73]
	v_mfma_f32_16x16x32_bf16 v[66:69], v[232:235], v[188:191], v[66:69]
	v_mfma_f32_16x16x32_bf16 v[118:121], v[216:219], v[168:171], v[118:121]
	v_mfma_f32_16x16x32_bf16 v[114:117], v[236:239], v[168:171], v[114:117]
	v_mfma_f32_16x16x32_bf16 v[102:105], v[216:219], v[176:179], v[102:105]
	v_mfma_f32_16x16x32_bf16 v[94:97], v[236:239], v[176:179], v[94:97]
	v_mfma_f32_16x16x32_bf16 v[86:89], v[216:219], v[184:187], v[86:89]
	v_mfma_f32_16x16x32_bf16 v[78:81], v[236:239], v[184:187], v[78:81]
	v_mfma_f32_16x16x32_bf16 v[70:73], v[216:219], v[192:195], v[70:73]
	v_mfma_f32_16x16x32_bf16 v[66:69], v[236:239], v[192:195], v[66:69]
	s_mov_b32 m0, s81
	v_lshl_add_u64 v[200:201], v[240:241], 0, s[14:15]
	s_barrier
	ds_read_b128 v[164:167], v147 offset:49152
	ds_read_b128 v[168:171], v147 offset:50176
	ds_read_b128 v[172:175], v147 offset:51200
	ds_read_b128 v[176:179], v147 offset:52224
	ds_read_b128 v[180:183], v147 offset:53248
	ds_read_b128 v[184:187], v147 offset:54272
	ds_read_b128 v[188:191], v147 offset:55296
	ds_read_b128 v[192:195], v147 offset:56320
	global_load_lds_dwordx4 v[200:201], off
	v_lshl_add_u64 v[200:201], v[242:243], 0, s[14:15]
	s_mov_b32 m0, s33
	s_nop 0
	global_load_lds_dwordx4 v[200:201], off
	s_barrier
	s_waitcnt lgkmcnt(0)
	s_waitcnt lgkmcnt(0)
	v_mfma_f32_16x16x32_bf16 v[62:65], v[148:151], v[164:167], v[62:65]
	v_mfma_f32_16x16x32_bf16 v[58:61], v[156:159], v[164:167], v[58:61]
	v_mfma_f32_16x16x32_bf16 v[50:53], v[148:151], v[172:175], v[50:53]
	v_mfma_f32_16x16x32_bf16 v[42:45], v[156:159], v[172:175], v[42:45]
	v_mfma_f32_16x16x32_bf16 v[34:37], v[148:151], v[180:183], v[34:37]
	v_mfma_f32_16x16x32_bf16 v[26:29], v[156:159], v[180:183], v[26:29]
	v_mfma_f32_16x16x32_bf16 v[18:21], v[148:151], v[188:191], v[18:21]
	v_mfma_f32_16x16x32_bf16 v[10:13], v[156:159], v[188:191], v[10:13]
	v_mfma_f32_16x16x32_bf16 v[62:65], v[152:155], v[168:171], v[62:65]
	v_mfma_f32_16x16x32_bf16 v[58:61], v[160:163], v[168:171], v[58:61]
	v_mfma_f32_16x16x32_bf16 v[50:53], v[152:155], v[176:179], v[50:53]
	v_mfma_f32_16x16x32_bf16 v[42:45], v[160:163], v[176:179], v[42:45]
	v_mfma_f32_16x16x32_bf16 v[34:37], v[152:155], v[184:187], v[34:37]
	v_mfma_f32_16x16x32_bf16 v[26:29], v[160:163], v[184:187], v[26:29]
	v_mfma_f32_16x16x32_bf16 v[18:21], v[152:155], v[192:195], v[18:21]
	v_mfma_f32_16x16x32_bf16 v[10:13], v[160:163], v[192:195], v[10:13]
	s_barrier
	s_add_u32 s36, s48, 0x100080
	s_addc_u32 s37, s49, 0
	s_add_i32 s31, s50, s90
	s_mov_b32 m0, s31
	s_nop 0
	global_load_lds_dwordx4 v134, s[36:37]
	s_add_i32 m0, s31, 0x2000
	s_nop 0
	global_load_lds_dwordx4 v130, s[36:37]
	s_waitcnt vmcnt(6)
	s_barrier
	v_mfma_f32_16x16x32_bf16 v[54:57], v[196:199], v[164:167], v[54:57]
	v_mfma_f32_16x16x32_bf16 v[46:49], v[232:235], v[164:167], v[46:49]
	v_mfma_f32_16x16x32_bf16 v[38:41], v[196:199], v[172:175], v[38:41]
	v_mfma_f32_16x16x32_bf16 v[30:33], v[232:235], v[172:175], v[30:33]
	v_mfma_f32_16x16x32_bf16 v[22:25], v[196:199], v[180:183], v[22:25]
	v_mfma_f32_16x16x32_bf16 v[14:17], v[232:235], v[180:183], v[14:17]
	v_mfma_f32_16x16x32_bf16 v[6:9], v[196:199], v[188:191], v[6:9]
	v_mfma_f32_16x16x32_bf16 v[2:5], v[232:235], v[188:191], v[2:5]
	v_mfma_f32_16x16x32_bf16 v[54:57], v[216:219], v[168:171], v[54:57]
	v_mfma_f32_16x16x32_bf16 v[46:49], v[236:239], v[168:171], v[46:49]
	v_mfma_f32_16x16x32_bf16 v[38:41], v[216:219], v[176:179], v[38:41]
	v_mfma_f32_16x16x32_bf16 v[30:33], v[236:239], v[176:179], v[30:33]
	v_mfma_f32_16x16x32_bf16 v[22:25], v[216:219], v[184:187], v[22:25]
	v_mfma_f32_16x16x32_bf16 v[14:17], v[236:239], v[184:187], v[14:17]
	v_mfma_f32_16x16x32_bf16 v[6:9], v[216:219], v[192:195], v[6:9]
	v_mfma_f32_16x16x32_bf16 v[2:5], v[236:239], v[192:195], v[2:5]
	s_add_i32 s13, s13, 2
	s_add_u32 s46, s46, 0x100
	s_addc_u32 s47, s47, 0
	s_cmp_gt_u32 s13, 61
	s_barrier
	s_cbranch_scc0 .LBB0_218
	s_add_u32 s24, s24, 0xffffff00
	s_addc_u32 s25, s25, -1
	s_andn2_b64 vcc, exec, s[40:41]
	s_cbranch_vccnz .LBB0_221
	v_mov_b32_e32 v2, 0
	s_mov_b32 s16, s20
	s_mov_b32 s30, s22
	s_mov_b64 s[18:19], s[44:45]
	s_mov_b32 s12, s83
	v_mov_b32_e32 v3, v2
	v_mov_b32_e32 v4, v2
	v_mov_b32_e32 v5, v2
	v_mov_b32_e32 v6, v2
	v_mov_b32_e32 v7, v2
	v_mov_b32_e32 v8, v2
	v_mov_b32_e32 v9, v2
	v_mov_b32_e32 v14, v2
	v_mov_b32_e32 v15, v2
	v_mov_b32_e32 v16, v2
	v_mov_b32_e32 v17, v2
	v_mov_b32_e32 v22, v2
	v_mov_b32_e32 v23, v2
	v_mov_b32_e32 v24, v2
	v_mov_b32_e32 v25, v2
	v_mov_b32_e32 v30, v2
	v_mov_b32_e32 v31, v2
	v_mov_b32_e32 v32, v2
	v_mov_b32_e32 v33, v2
	v_mov_b32_e32 v38, v2
	v_mov_b32_e32 v39, v2
	v_mov_b32_e32 v40, v2
	v_mov_b32_e32 v41, v2
	v_mov_b32_e32 v46, v2
	v_mov_b32_e32 v47, v2
	v_mov_b32_e32 v48, v2
	v_mov_b32_e32 v49, v2
	v_mov_b32_e32 v54, v2
	v_mov_b32_e32 v55, v2
	v_mov_b32_e32 v56, v2
	v_mov_b32_e32 v57, v2
	v_mov_b32_e32 v10, v2
	v_mov_b32_e32 v11, v2
	v_mov_b32_e32 v12, v2
	v_mov_b32_e32 v13, v2
	v_mov_b32_e32 v18, v2
	v_mov_b32_e32 v19, v2
	v_mov_b32_e32 v20, v2
	v_mov_b32_e32 v21, v2
	v_mov_b32_e32 v26, v2
	v_mov_b32_e32 v27, v2
	v_mov_b32_e32 v28, v2
	v_mov_b32_e32 v29, v2
	v_mov_b32_e32 v34, v2
	v_mov_b32_e32 v35, v2
	v_mov_b32_e32 v36, v2
	v_mov_b32_e32 v37, v2
	v_mov_b32_e32 v42, v2
	v_mov_b32_e32 v43, v2
	v_mov_b32_e32 v44, v2
	v_mov_b32_e32 v45, v2
	v_mov_b32_e32 v50, v2
	v_mov_b32_e32 v51, v2
	v_mov_b32_e32 v52, v2
	v_mov_b32_e32 v53, v2
	v_mov_b32_e32 v58, v2
	v_mov_b32_e32 v59, v2
	v_mov_b32_e32 v60, v2
	v_mov_b32_e32 v61, v2
	v_mov_b32_e32 v62, v2
	v_mov_b32_e32 v63, v2
	v_mov_b32_e32 v64, v2
	v_mov_b32_e32 v65, v2
	v_mov_b32_e32 v66, v2
	v_mov_b32_e32 v67, v2
	v_mov_b32_e32 v68, v2
	v_mov_b32_e32 v69, v2
	v_mov_b32_e32 v70, v2
	v_mov_b32_e32 v71, v2
	v_mov_b32_e32 v72, v2
	v_mov_b32_e32 v73, v2
	v_mov_b32_e32 v78, v2
	v_mov_b32_e32 v79, v2
	v_mov_b32_e32 v80, v2
	v_mov_b32_e32 v81, v2
	v_mov_b32_e32 v86, v2
	v_mov_b32_e32 v87, v2
	v_mov_b32_e32 v88, v2
	v_mov_b32_e32 v89, v2
	v_mov_b32_e32 v94, v2
	v_mov_b32_e32 v95, v2
	v_mov_b32_e32 v96, v2
	v_mov_b32_e32 v97, v2
	v_mov_b32_e32 v102, v2
	v_mov_b32_e32 v103, v2
	v_mov_b32_e32 v104, v2
	v_mov_b32_e32 v105, v2
	v_mov_b32_e32 v114, v2
	v_mov_b32_e32 v115, v2
	v_mov_b32_e32 v116, v2
	v_mov_b32_e32 v117, v2
	v_mov_b32_e32 v118, v2
	v_mov_b32_e32 v119, v2
	v_mov_b32_e32 v120, v2
	v_mov_b32_e32 v121, v2
	v_mov_b32_e32 v74, v2
	v_mov_b32_e32 v75, v2
	v_mov_b32_e32 v76, v2
	v_mov_b32_e32 v77, v2
	v_mov_b32_e32 v82, v2
	v_mov_b32_e32 v83, v2
	v_mov_b32_e32 v84, v2
	v_mov_b32_e32 v85, v2
	v_mov_b32_e32 v90, v2
	v_mov_b32_e32 v91, v2
	v_mov_b32_e32 v92, v2
	v_mov_b32_e32 v93, v2
	v_mov_b32_e32 v98, v2
	v_mov_b32_e32 v99, v2
	v_mov_b32_e32 v100, v2
	v_mov_b32_e32 v101, v2
	v_mov_b32_e32 v106, v2
	v_mov_b32_e32 v107, v2
	v_mov_b32_e32 v108, v2
	v_mov_b32_e32 v109, v2
	v_mov_b32_e32 v110, v2
	v_mov_b32_e32 v111, v2
	v_mov_b32_e32 v112, v2
	v_mov_b32_e32 v113, v2
	v_mov_b32_e32 v122, v2
	v_mov_b32_e32 v123, v2
	v_mov_b32_e32 v124, v2
	v_mov_b32_e32 v125, v2
	v_mov_b32_e32 v126, v2
	v_mov_b32_e32 v127, v2
	v_mov_b32_e32 v128, v2
	v_mov_b32_e32 v129, v2
	s_branch .LBB0_222

.LBB0_259:
	s_add_u32 s13, s40, 0xfff80080
	s_addc_u32 s36, s41, -1
	s_add_i32 s37, 0, 0x10000
	v_add_u32_e32 v146, s37, v147
	ds_read_b128 v[142:145], v146
	ds_read_b128 v[152:155], v146 offset:1024
	ds_read_b128 v[156:159], v146 offset:2048
	ds_read_b128 v[160:163], v146 offset:3072
	s_cmp_eq_u32 s81, 28
	s_cselect_b32 s45, s19, s36
	s_cselect_b32 s44, s24, s13
	s_cselect_b32 s43, s17, s80
	s_cselect_b32 s42, s25, s33
	s_add_i32 m0, s69, 0xc000
	ds_read_b128 v[164:167], v150
	ds_read_b128 v[168:171], v150 offset:1024
	ds_read_b128 v[172:175], v150 offset:2048
	ds_read_b128 v[176:179], v150 offset:3072
	ds_read_b128 v[180:183], v150 offset:4096
	ds_read_b128 v[184:187], v150 offset:5120
	ds_read_b128 v[188:191], v150 offset:6144
	ds_read_b128 v[192:195], v150 offset:7168
	global_load_lds_dwordx4 v138, s[40:41]
	s_add_i32 m0, s69, 0xe000
	s_nop 0
	global_load_lds_dwordx4 v140, s[40:41]
	s_waitcnt lgkmcnt(8)
	s_barrier
	s_waitcnt lgkmcnt(0)
	s_waitcnt lgkmcnt(0)
	v_mfma_f32_16x16x32_bf16 v[126:129], v[142:145], v[164:167], v[126:129]
	v_mfma_f32_16x16x32_bf16 v[122:125], v[156:159], v[164:167], v[122:125]
	v_mfma_f32_16x16x32_bf16 v[110:113], v[142:145], v[172:175], v[110:113]
	v_mfma_f32_16x16x32_bf16 v[106:109], v[156:159], v[172:175], v[106:109]
	v_mfma_f32_16x16x32_bf16 v[94:97], v[142:145], v[180:183], v[94:97]
	v_mfma_f32_16x16x32_bf16 v[90:93], v[156:159], v[180:183], v[90:93]
	v_mfma_f32_16x16x32_bf16 v[78:81], v[142:145], v[188:191], v[78:81]
	v_mfma_f32_16x16x32_bf16 v[74:77], v[156:159], v[188:191], v[74:77]
	v_mfma_f32_16x16x32_bf16 v[126:129], v[152:155], v[168:171], v[126:129]
	v_mfma_f32_16x16x32_bf16 v[122:125], v[160:163], v[168:171], v[122:125]
	v_mfma_f32_16x16x32_bf16 v[110:113], v[152:155], v[176:179], v[110:113]
	v_mfma_f32_16x16x32_bf16 v[106:109], v[160:163], v[176:179], v[106:109]
	v_mfma_f32_16x16x32_bf16 v[94:97], v[152:155], v[184:187], v[94:97]
	v_mfma_f32_16x16x32_bf16 v[90:93], v[160:163], v[184:187], v[90:93]
	v_mfma_f32_16x16x32_bf16 v[78:81], v[152:155], v[192:195], v[78:81]
	v_mfma_f32_16x16x32_bf16 v[74:77], v[160:163], v[192:195], v[74:77]
	s_barrier
	s_add_i32 s13, 0, 0x14000
	s_add_i32 s36, s37, s48
	v_add_u32_e32 v146, s13, v147
	v_lshl_add_u64 v[204:205], s[42:43], 0, v[134:135]
	s_mov_b32 m0, s36
	ds_read_b128 v[196:199], v146
	ds_read_b128 v[200:203], v146 offset:1024
	ds_read_b128 v[216:219], v146 offset:2048
	ds_read_b128 v[232:235], v146 offset:3072
	global_load_lds_dwordx4 v[204:205], off
	v_lshl_add_u64 v[236:237], s[42:43], 0, v[130:131]
	s_add_i32 m0, s36, 0x2000
	s_nop 0
	global_load_lds_dwordx4 v[236:237], off
	s_barrier
	s_waitcnt lgkmcnt(0)
	s_waitcnt lgkmcnt(0)
	v_mfma_f32_16x16x32_bf16 v[118:121], v[196:199], v[164:167], v[118:121]
	v_mfma_f32_16x16x32_bf16 v[114:117], v[216:219], v[164:167], v[114:117]
	v_mfma_f32_16x16x32_bf16 v[102:105], v[196:199], v[172:175], v[102:105]
	v_mfma_f32_16x16x32_bf16 v[98:101], v[216:219], v[172:175], v[98:101]
	v_mfma_f32_16x16x32_bf16 v[86:89], v[196:199], v[180:183], v[86:89]
	v_mfma_f32_16x16x32_bf16 v[82:85], v[216:219], v[180:183], v[82:85]
	v_mfma_f32_16x16x32_bf16 v[70:73], v[196:199], v[188:191], v[70:73]
	v_mfma_f32_16x16x32_bf16 v[66:69], v[216:219], v[188:191], v[66:69]
	v_mfma_f32_16x16x32_bf16 v[118:121], v[200:203], v[168:171], v[118:121]
	v_mfma_f32_16x16x32_bf16 v[114:117], v[232:235], v[168:171], v[114:117]
	v_mfma_f32_16x16x32_bf16 v[102:105], v[200:203], v[176:179], v[102:105]
	v_mfma_f32_16x16x32_bf16 v[98:101], v[232:235], v[176:179], v[98:101]
	v_mfma_f32_16x16x32_bf16 v[86:89], v[200:203], v[184:187], v[86:89]
	v_mfma_f32_16x16x32_bf16 v[82:85], v[232:235], v[184:187], v[82:85]
	v_mfma_f32_16x16x32_bf16 v[70:73], v[200:203], v[192:195], v[70:73]
	v_mfma_f32_16x16x32_bf16 v[66:69], v[232:235], v[192:195], v[66:69]
	s_mov_b32 m0, s69
	v_lshl_add_u64 v[238:239], s[44:45], 0, v[136:137]
	s_barrier
	ds_read_b128 v[164:167], v150 offset:16384
	ds_read_b128 v[168:171], v150 offset:17408
	ds_read_b128 v[172:175], v150 offset:18432
	ds_read_b128 v[176:179], v150 offset:19456
	ds_read_b128 v[180:183], v150 offset:20480
	ds_read_b128 v[184:187], v150 offset:21504
	ds_read_b128 v[188:191], v150 offset:22528
	ds_read_b128 v[192:195], v150 offset:23552
	global_load_lds_dwordx4 v[238:239], off
	v_lshl_add_u64 v[240:241], s[44:45], 0, v[132:133]
	s_mov_b32 m0, s86
	s_nop 0
	global_load_lds_dwordx4 v[240:241], off
	s_barrier
	s_waitcnt lgkmcnt(0)
	s_waitcnt lgkmcnt(0)
	v_mfma_f32_16x16x32_bf16 v[62:65], v[142:145], v[164:167], v[62:65]
	v_mfma_f32_16x16x32_bf16 v[58:61], v[156:159], v[164:167], v[58:61]
	v_mfma_f32_16x16x32_bf16 v[46:49], v[142:145], v[172:175], v[46:49]
	v_mfma_f32_16x16x32_bf16 v[42:45], v[156:159], v[172:175], v[42:45]
	v_mfma_f32_16x16x32_bf16 v[30:33], v[142:145], v[180:183], v[30:33]
	v_mfma_f32_16x16x32_bf16 v[26:29], v[156:159], v[180:183], v[26:29]
	v_mfma_f32_16x16x32_bf16 v[14:17], v[142:145], v[188:191], v[14:17]
	v_mfma_f32_16x16x32_bf16 v[10:13], v[156:159], v[188:191], v[10:13]
	v_mfma_f32_16x16x32_bf16 v[62:65], v[152:155], v[168:171], v[62:65]
	v_mfma_f32_16x16x32_bf16 v[58:61], v[160:163], v[168:171], v[58:61]
	v_mfma_f32_16x16x32_bf16 v[46:49], v[152:155], v[176:179], v[46:49]
	v_mfma_f32_16x16x32_bf16 v[42:45], v[160:163], v[176:179], v[42:45]
	v_mfma_f32_16x16x32_bf16 v[30:33], v[152:155], v[184:187], v[30:33]
	v_mfma_f32_16x16x32_bf16 v[26:29], v[160:163], v[184:187], v[26:29]
	v_mfma_f32_16x16x32_bf16 v[14:17], v[152:155], v[192:195], v[14:17]
	v_mfma_f32_16x16x32_bf16 v[10:13], v[160:163], v[192:195], v[10:13]
	s_barrier
	s_add_u32 s96, s42, 0x80000
	s_addc_u32 s97, s43, 0
	s_add_i32 s13, s13, s48
	s_mov_b32 m0, s13
	s_nop 0
	global_load_lds_dwordx4 v134, s[96:97]
	s_add_i32 m0, s13, 0x2000
	s_nop 0
	global_load_lds_dwordx4 v130, s[96:97]
	s_waitcnt vmcnt(6)
	s_barrier
	v_mfma_f32_16x16x32_bf16 v[54:57], v[196:199], v[164:167], v[54:57]
	v_mfma_f32_16x16x32_bf16 v[50:53], v[216:219], v[164:167], v[50:53]
	v_mfma_f32_16x16x32_bf16 v[38:41], v[196:199], v[172:175], v[38:41]
	v_mfma_f32_16x16x32_bf16 v[34:37], v[216:219], v[172:175], v[34:37]
	v_mfma_f32_16x16x32_bf16 v[22:25], v[196:199], v[180:183], v[22:25]
	v_mfma_f32_16x16x32_bf16 v[18:21], v[216:219], v[180:183], v[18:21]
	v_mfma_f32_16x16x32_bf16 v[6:9], v[196:199], v[188:191], v[6:9]
	v_mfma_f32_16x16x32_bf16 v[2:5], v[216:219], v[188:191], v[2:5]
	v_mfma_f32_16x16x32_bf16 v[54:57], v[200:203], v[168:171], v[54:57]
	v_mfma_f32_16x16x32_bf16 v[50:53], v[232:235], v[168:171], v[50:53]
	v_mfma_f32_16x16x32_bf16 v[38:41], v[200:203], v[176:179], v[38:41]
	v_mfma_f32_16x16x32_bf16 v[34:37], v[232:235], v[176:179], v[34:37]
	v_mfma_f32_16x16x32_bf16 v[22:25], v[200:203], v[184:187], v[22:25]
	v_mfma_f32_16x16x32_bf16 v[18:21], v[232:235], v[184:187], v[18:21]
	v_mfma_f32_16x16x32_bf16 v[6:9], v[200:203], v[192:195], v[6:9]
	v_mfma_f32_16x16x32_bf16 v[2:5], v[232:235], v[192:195], v[2:5]
	s_add_i32 s13, 0, 0x18000
	v_add_u32_e32 v146, s13, v147
	s_barrier
	ds_read_b128 v[142:145], v146
	ds_read_b128 v[152:155], v146 offset:1024
	ds_read_b128 v[156:159], v146 offset:2048
	ds_read_b128 v[160:163], v146 offset:3072
	s_add_u32 s44, s44, 0x80000
	s_addc_u32 s45, s45, 0
	s_mov_b32 m0, s87
	ds_read_b128 v[164:167], v150 offset:32768
	ds_read_b128 v[168:171], v150 offset:33792
	ds_read_b128 v[172:175], v150 offset:34816
	ds_read_b128 v[176:179], v150 offset:35840
	ds_read_b128 v[180:183], v150 offset:36864
	ds_read_b128 v[184:187], v150 offset:37888
	ds_read_b128 v[188:191], v150 offset:38912
	ds_read_b128 v[192:195], v150 offset:39936
	global_load_lds_dwordx4 v136, s[44:45]
	s_mov_b32 m0, s90
	s_nop 0
	global_load_lds_dwordx4 v132, s[44:45]
	s_waitcnt lgkmcnt(8)
	s_barrier
	s_waitcnt lgkmcnt(0)
	s_waitcnt lgkmcnt(0)
	v_mfma_f32_16x16x32_bf16 v[126:129], v[142:145], v[164:167], v[126:129]
	v_mfma_f32_16x16x32_bf16 v[122:125], v[156:159], v[164:167], v[122:125]
	v_mfma_f32_16x16x32_bf16 v[110:113], v[142:145], v[172:175], v[110:113]
	v_mfma_f32_16x16x32_bf16 v[106:109], v[156:159], v[172:175], v[106:109]
	v_mfma_f32_16x16x32_bf16 v[94:97], v[142:145], v[180:183], v[94:97]
	v_mfma_f32_16x16x32_bf16 v[90:93], v[156:159], v[180:183], v[90:93]
	v_mfma_f32_16x16x32_bf16 v[78:81], v[142:145], v[188:191], v[78:81]
	v_mfma_f32_16x16x32_bf16 v[74:77], v[156:159], v[188:191], v[74:77]
	v_mfma_f32_16x16x32_bf16 v[126:129], v[152:155], v[168:171], v[126:129]
	v_mfma_f32_16x16x32_bf16 v[122:125], v[160:163], v[168:171], v[122:125]
	v_mfma_f32_16x16x32_bf16 v[110:113], v[152:155], v[176:179], v[110:113]
	v_mfma_f32_16x16x32_bf16 v[106:109], v[160:163], v[176:179], v[106:109]
	v_mfma_f32_16x16x32_bf16 v[94:97], v[152:155], v[184:187], v[94:97]
	v_mfma_f32_16x16x32_bf16 v[90:93], v[160:163], v[184:187], v[90:93]
	v_mfma_f32_16x16x32_bf16 v[78:81], v[152:155], v[192:195], v[78:81]
	v_mfma_f32_16x16x32_bf16 v[74:77], v[160:163], v[192:195], v[74:77]
	s_barrier
	s_add_i32 s36, 0, 0x1c000
	s_add_i32 s13, s13, s48
	v_add_u32_e32 v146, s36, v147
	v_lshl_add_u64 v[204:205], v[204:205], 0, s[14:15]
	s_mov_b32 m0, s13
	ds_read_b128 v[196:199], v146
	ds_read_b128 v[200:203], v146 offset:1024
	ds_read_b128 v[216:219], v146 offset:2048
	ds_read_b128 v[232:235], v146 offset:3072
	global_load_lds_dwordx4 v[204:205], off
	v_lshl_add_u64 v[204:205], v[236:237], 0, s[14:15]
	s_add_i32 m0, s13, 0x2000
	s_nop 0
	global_load_lds_dwordx4 v[204:205], off
	s_barrier
	s_waitcnt lgkmcnt(0)
	s_waitcnt lgkmcnt(0)
	v_mfma_f32_16x16x32_bf16 v[118:121], v[196:199], v[164:167], v[118:121]
	v_mfma_f32_16x16x32_bf16 v[114:117], v[216:219], v[164:167], v[114:117]
	v_mfma_f32_16x16x32_bf16 v[102:105], v[196:199], v[172:175], v[102:105]
	v_mfma_f32_16x16x32_bf16 v[98:101], v[216:219], v[172:175], v[98:101]
	v_mfma_f32_16x16x32_bf16 v[86:89], v[196:199], v[180:183], v[86:89]
	v_mfma_f32_16x16x32_bf16 v[82:85], v[216:219], v[180:183], v[82:85]
	v_mfma_f32_16x16x32_bf16 v[70:73], v[196:199], v[188:191], v[70:73]
	v_mfma_f32_16x16x32_bf16 v[66:69], v[216:219], v[188:191], v[66:69]
	v_mfma_f32_16x16x32_bf16 v[118:121], v[200:203], v[168:171], v[118:121]
	v_mfma_f32_16x16x32_bf16 v[114:117], v[232:235], v[168:171], v[114:117]
	v_mfma_f32_16x16x32_bf16 v[102:105], v[200:203], v[176:179], v[102:105]
	v_mfma_f32_16x16x32_bf16 v[98:101], v[232:235], v[176:179], v[98:101]
	v_mfma_f32_16x16x32_bf16 v[86:89], v[200:203], v[184:187], v[86:89]
	v_mfma_f32_16x16x32_bf16 v[82:85], v[232:235], v[184:187], v[82:85]
	v_mfma_f32_16x16x32_bf16 v[70:73], v[200:203], v[192:195], v[70:73]
	v_mfma_f32_16x16x32_bf16 v[66:69], v[232:235], v[192:195], v[66:69]
	s_mov_b32 m0, s91
	v_lshl_add_u64 v[204:205], v[238:239], 0, s[14:15]
	s_barrier
	ds_read_b128 v[164:167], v150 offset:49152
	ds_read_b128 v[168:171], v150 offset:50176
	ds_read_b128 v[172:175], v150 offset:51200
	ds_read_b128 v[176:179], v150 offset:52224
	ds_read_b128 v[180:183], v150 offset:53248
	ds_read_b128 v[184:187], v150 offset:54272
	ds_read_b128 v[188:191], v150 offset:55296
	ds_read_b128 v[192:195], v150 offset:56320
	global_load_lds_dwordx4 v[204:205], off
	v_lshl_add_u64 v[204:205], v[240:241], 0, s[14:15]
	s_mov_b32 m0, s26
	s_nop 0
	global_load_lds_dwordx4 v[204:205], off
	s_barrier
	s_waitcnt lgkmcnt(0)
	s_waitcnt lgkmcnt(0)
	v_mfma_f32_16x16x32_bf16 v[62:65], v[142:145], v[164:167], v[62:65]
	v_mfma_f32_16x16x32_bf16 v[58:61], v[156:159], v[164:167], v[58:61]
	v_mfma_f32_16x16x32_bf16 v[46:49], v[142:145], v[172:175], v[46:49]
	v_mfma_f32_16x16x32_bf16 v[42:45], v[156:159], v[172:175], v[42:45]
	v_mfma_f32_16x16x32_bf16 v[30:33], v[142:145], v[180:183], v[30:33]
	v_mfma_f32_16x16x32_bf16 v[26:29], v[156:159], v[180:183], v[26:29]
	v_mfma_f32_16x16x32_bf16 v[14:17], v[142:145], v[188:191], v[14:17]
	v_mfma_f32_16x16x32_bf16 v[10:13], v[156:159], v[188:191], v[10:13]
	v_mfma_f32_16x16x32_bf16 v[62:65], v[152:155], v[168:171], v[62:65]
	v_mfma_f32_16x16x32_bf16 v[58:61], v[160:163], v[168:171], v[58:61]
	v_mfma_f32_16x16x32_bf16 v[46:49], v[152:155], v[176:179], v[46:49]
	v_mfma_f32_16x16x32_bf16 v[42:45], v[160:163], v[176:179], v[42:45]
	v_mfma_f32_16x16x32_bf16 v[30:33], v[152:155], v[184:187], v[30:33]
	v_mfma_f32_16x16x32_bf16 v[26:29], v[160:163], v[184:187], v[26:29]
	v_mfma_f32_16x16x32_bf16 v[14:17], v[152:155], v[192:195], v[14:17]
	v_mfma_f32_16x16x32_bf16 v[10:13], v[160:163], v[192:195], v[10:13]
	s_barrier
	s_add_u32 s42, s42, 0x80080
	s_addc_u32 s43, s43, 0
	s_add_i32 s13, s36, s48
	s_mov_b32 m0, s13
	s_nop 0
	global_load_lds_dwordx4 v134, s[42:43]
	s_add_i32 m0, s13, 0x2000
	s_nop 0
	global_load_lds_dwordx4 v130, s[42:43]
	s_waitcnt vmcnt(6)
	s_barrier
	v_mfma_f32_16x16x32_bf16 v[54:57], v[196:199], v[164:167], v[54:57]
	v_mfma_f32_16x16x32_bf16 v[50:53], v[216:219], v[164:167], v[50:53]
	v_mfma_f32_16x16x32_bf16 v[38:41], v[196:199], v[172:175], v[38:41]
	v_mfma_f32_16x16x32_bf16 v[34:37], v[216:219], v[172:175], v[34:37]
	v_mfma_f32_16x16x32_bf16 v[22:25], v[196:199], v[180:183], v[22:25]
	v_mfma_f32_16x16x32_bf16 v[18:21], v[216:219], v[180:183], v[18:21]
	v_mfma_f32_16x16x32_bf16 v[6:9], v[196:199], v[188:191], v[6:9]
	v_mfma_f32_16x16x32_bf16 v[2:5], v[216:219], v[188:191], v[2:5]
	v_mfma_f32_16x16x32_bf16 v[54:57], v[200:203], v[168:171], v[54:57]
	v_mfma_f32_16x16x32_bf16 v[50:53], v[232:235], v[168:171], v[50:53]
	v_mfma_f32_16x16x32_bf16 v[38:41], v[200:203], v[176:179], v[38:41]
	v_mfma_f32_16x16x32_bf16 v[34:37], v[232:235], v[176:179], v[34:37]
	v_mfma_f32_16x16x32_bf16 v[22:25], v[200:203], v[184:187], v[22:25]
	v_mfma_f32_16x16x32_bf16 v[18:21], v[232:235], v[184:187], v[18:21]
	v_mfma_f32_16x16x32_bf16 v[6:9], v[200:203], v[192:195], v[6:9]
	v_mfma_f32_16x16x32_bf16 v[2:5], v[232:235], v[192:195], v[2:5]
	s_add_i32 s81, s81, 2
	s_add_u32 s40, s40, 0x100
	s_addc_u32 s41, s41, 0
	s_add_u32 s33, s33, 0x100
	s_addc_u32 s80, s80, 0
	s_cmp_gt_u32 s81, 29
	s_barrier
	s_cbranch_scc0 .LBB0_259
	s_cmp_lg_u32 s12, s46
	v_lshl_add_u32 v144, s12, 8, v1
	s_cselect_b64 s[42:43], -1, 0
	s_mov_b64 s[24:25], -1
	s_and_b64 vcc, exec, s[42:43]
	v_ashrrev_i32_e32 v145, 31, v144
	s_cbranch_vccz .LBB0_262
	v_lshl_add_u64 v[142:143], v[144:145], 2, s[0:1]
	v_add_co_u32_e32 v152, vcc, 0x8000, v142
	global_load_dword v146, v[142:143], off
	s_nop 0
	v_addc_co_u32_e32 v153, vcc, 0, v143, vcc
	global_load_dword v151, v[152:153], off
	v_add_co_u32_e32 v152, vcc, 0x10000, v142
	s_mov_b64 s[24:25], 0
	s_nop 0
	v_addc_co_u32_e32 v153, vcc, 0, v143, vcc
	s_waitcnt vmcnt(0)
	v_add_f32_e32 v146, 0, v146
	v_add_f32_e32 v146, v146, v151
	global_load_dword v151, v[152:153], off
	v_add_co_u32_e32 v152, vcc, 0x18000, v142
	s_waitcnt vmcnt(0)
	v_add_f32_e32 v146, v146, v151
	v_addc_co_u32_e32 v153, vcc, 0, v143, vcc
	global_load_dword v151, v[152:153], off
	v_add_co_u32_e32 v152, vcc, s5, v142
	s_waitcnt vmcnt(0)
	v_add_f32_e32 v146, v146, v151
	v_addc_co_u32_e32 v153, vcc, 0, v143, vcc
	global_load_dword v151, v[152:153], off
	v_add_co_u32_e32 v152, vcc, 0x28000, v142
	s_waitcnt vmcnt(0)
	v_add_f32_e32 v146, v146, v151
	v_addc_co_u32_e32 v153, vcc, 0, v143, vcc
	global_load_dword v151, v[152:153], off
	v_add_co_u32_e32 v152, vcc, 0x30000, v142
	s_waitcnt vmcnt(0)
	v_add_f32_e32 v146, v146, v151
	v_addc_co_u32_e32 v153, vcc, 0, v143, vcc
	v_add_co_u32_e32 v142, vcc, 0x38000, v142
	global_load_dword v151, v[152:153], off
	s_nop 0
	v_addc_co_u32_e32 v143, vcc, 0, v143, vcc
	global_load_dword v142, v[142:143], off
	s_waitcnt vmcnt(0)
	v_add_f32_e32 v146, v146, v151
	v_add_f32_e32 v142, v146, v142
	v_fmamk_f32 v142, v142, 0x3a000000, v223
	v_cmp_gt_f32_e32 vcc, s4, v142
	v_mul_f32_e32 v143, 0x4b800000, v142
	s_nop 0
	v_cndmask_b32_e32 v142, v142, v143, vcc
	v_rsq_f32_e32 v142, v142
	s_nop 0
	v_mul_f32_e32 v143, 0x45800000, v142
	v_cndmask_b32_e32 v146, v142, v143, vcc
